# barrier XCD leader: L1 invalidate issued with the top-level arrival atomic (right after the L2 writeback) instead of before the first release poll
# baseline (speedup 1.0000x reference)
.LBB0_1147:
	s_mov_b64 s[6:7], exec
	buffer_wbl2 sc1
	s_waitcnt lgkmcnt(0)
	s_waitcnt vmcnt(0)
	buffer_inv sc1
	v_mbcnt_lo_u32_b32 v0, s6, 0
	v_mbcnt_hi_u32_b32 v0, s7, v0
	v_cmp_eq_u32_e32 vcc, 0, v0
	s_and_saveexec_b64 s[8:9], vcc
	s_cbranch_execz .LBB0_1149
	s_bcnt1_i32_b64 s6, s[6:7]
	v_mov_b32_e32 v3, s6
	v_mov_b32_e32 v4, 0x83000
	global_atomic_add v3, v4, v3, s[2:3] offset:1024 sc0

.LBB0_1163:
	s_or_b64 exec, exec, s[2:3]
	s_mov_b64 s[2:3], exec
	v_mbcnt_lo_u32_b32 v0, s2, 0
	v_mbcnt_hi_u32_b32 v0, s3, v0
	v_cmp_eq_u32_e32 vcc, 0, v0
	s_and_saveexec_b64 s[6:7], vcc
	s_getpc_b64 s[98:99]
